# GEMM phase prologues: the second staging batch (K-tile 1) is issued before the first wait and workgroup barrier instead of after (wait count 2 to 8)
# baseline (speedup 1.0000x reference)
; #define PG8_STAGE(bufoff, gbase, voff) do { _Pragma("unroll") for (int _i = 0; _i < 2; ++_i) \
;         __builtin_amdgcn_global_load_lds((const unsigned*)((const char*)(gbase) + (voff)[_i]), (PG8_LAS unsigned*)(lds + (bufoff) + ldsw + _i * 8192), 16, 0, 0); } while (0)
; #define PG8_WAIT_V(n) asm volatile("s_waitcnt vmcnt(" #n ")" ::: "memory")
; #define PG8_BAR __builtin_amdgcn_s_barrier()
; #define LAS __attribute__((address_space(3)))
; template <class Epi, class Sched, bool ALIGN_EPI = false, bool SP2 = false>
; __device__ __forceinline__ void gemm_phase(PG8_LAS unsigned char* lds, const Gemm g, const Sched& S, const Epi& E) {
;     ...
;         PG8_STAGE(PG8_SB(0, 0), cB, voffB); PG8_STAGE(PG8_SB(0, 1), cB + hstep, voffB); PG8_STAGE(PG8_SA(0, 0), cA, voffA); PG8_STAGE(PG8_SA(0, 1), cA + hstep, voffA);
;         if (wr == 1) PG8_BAR;
;         PG8_WAIT_V(2); PG8_BAR;
;         PG8_STAGE(PG8_SB(1, 0), cB + kstep, voffB); PG8_STAGE(PG8_SA(1, 0), cA + kstep, voffA); PG8_STAGE(PG8_SB(1, 1), cB + hstep + kstep, voffB);
; __device__ __forceinline__ void scan_item(const Params& p, LAS unsigned char* lds, int bh, int tid, int lane, int wave) {
;     const float* logf = (const float*)(p.ws + WS_LOGF); const int b = bh >> 3, h = bh & 7;
;     LAS float* wt = (LAS float*)lds;
;     float a[4];
; #pragma unroll
;     for (int i = 0; i < 4; ++i) a[i] = logf[((size_t)(b * S_ + 4 * tid + i)) * 8 + h];
;     a[1] += a[0]; a[2] += a[1]; a[3] += a[2];
;     float sc = a[3];
; #pragma unroll
;     for (int o = 1; o < 64; o <<= 1) { const float y = __shfl_up(sc, o); if (lane >= o) sc += y; }
;     if (lane == 63) wt[wave] = sc;
;     __syncthreads();
;     float off = sc - a[3];
;     for (int w = 0; w < wave; ++w) off += wt[w];
.LBB0_268:
	s_add_u32 s65, s36, 0x6000000
	s_addc_u32 s66, s37, 0
	s_add_u32 s12, s36, 0x7000000
	s_addc_u32 s0, s37, 0
	s_add_u32 s16, s36, 0x8000000
	s_mov_b64 s[38:39], 0x80
	s_addc_u32 s1, s37, 0
	s_and_b32 s67, s17, 3
	s_add_i32 m0, s56, 0x18000
	v_lshl_add_u64 v[6:7], v[6:7], 0, s[38:39]
	s_lshl_b32 s68, s13, 6
	s_lshl_b32 s13, s13, 13
	s_lshl_b32 s17, s67, 12
	global_load_lds_dwordx4 v[6:7], off
	v_lshl_add_u64 v[4:5], v[4:5], 0, s[38:39]
	s_add_i32 m0, s56, 0x1a000
	s_add_i32 s69, s56, 0x8000
	s_add_i32 s70, s56, 0xa000
	global_load_lds_dwordx4 v[4:5], off
	v_lshl_add_u64 v[2:3], v[2:3], 0, s[38:39]
	s_mov_b32 m0, s69
	s_add_u32 s18, s50, 0x40080
	global_load_lds_dwordx4 v[2:3], off
	v_lshl_add_u64 v[0:1], v[0:1], 0, s[38:39]
	s_mov_b32 m0, s70
	s_addc_u32 s19, s51, 0
	global_load_lds_dwordx4 v[0:1], off
	s_add_i32 m0, s56, 0x1c000
	v_lshl_add_u64 v[0:1], s[18:19], 0, v[132:133]
	global_load_lds_dwordx4 v[0:1], off
	v_lshl_add_u64 v[0:1], s[18:19], 0, v[128:129]
	s_add_i32 m0, s56, 0x1e000
	v_and_b32_e32 v156, 15, v12
	global_load_lds_dwordx4 v[0:1], off
	s_cmp_gt_i32 s2, 63
	s_cbranch_scc1 .Lscan_skip
	v_readfirstlane_b32 s76, v208
	s_and_b32 s74, s2, 7
	s_lshl_b32 s75, s2, 8
	s_and_b32 s75, s75, 0xfffff800
	s_lshl_b32 s74, s74, 2
	v_add_u32_e32 v16, s75, v96
	s_add_u32 s74, s36, s74
	s_addc_u32 s75, s37, 0
	v_or_b32_e32 v20, 1, v16
	s_add_u32 s78, s74, 0x100000
	v_ashrrev_i32_e32 v21, 31, v20
	s_addc_u32 s79, s75, 0
	v_ashrrev_i32_e32 v17, 31, v16
	v_lshlrev_b64 v[20:21], 5, v[20:21]
	v_lshlrev_b64 v[18:19], 5, v[16:17]
	v_lshl_add_u64 v[22:23], s[78:79], 0, v[20:21]
	v_or_b32_e32 v20, 2, v16
	v_or_b32_e32 v16, 3, v16
	v_ashrrev_i32_e32 v21, 31, v20
	v_ashrrev_i32_e32 v17, 31, v16
	v_lshl_add_u64 v[18:19], s[78:79], 0, v[18:19]
	v_lshlrev_b64 v[20:21], 5, v[20:21]
	v_lshlrev_b64 v[16:17], 5, v[16:17]
	v_lshl_add_u64 v[24:25], s[78:79], 0, v[20:21]
	v_lshl_add_u64 v[16:17], s[78:79], 0, v[16:17]
	global_load_dword v20, v[18:19], off
	global_load_dword v21, v[22:23], off
	global_load_dword v26, v[24:25], off
	global_load_dword v27, v[16:17], off
	v_mbcnt_hi_u32_b32 v19, -1, v209
	v_and_b32_e32 v22, 64, v19
	v_add_u32_e32 v16, -1, v19
	v_cmp_lt_i32_e32 vcc, v16, v22
	v_add_u32_e32 v24, -4, v19
	s_waitcnt vmcnt(2)
	v_add_f32_e32 v18, v20, v21
	v_cndmask_b32_e32 v16, v16, v19, vcc
	s_waitcnt vmcnt(1)
	v_add_f32_e32 v17, v26, v18
	v_lshlrev_b32_e32 v23, 2, v16
	s_waitcnt vmcnt(0)
	v_add_f32_e32 v16, v27, v17
	ds_bpermute_b32 v21, v23, v16
	v_add_u32_e32 v23, -2, v19
	v_cmp_lt_i32_e32 vcc, v23, v22
	s_waitcnt lgkmcnt(0)
	v_add_f32_e32 v21, v16, v21
	v_cndmask_b32_e32 v23, v23, v19, vcc
	v_cmp_eq_u32_e32 vcc, 0, v154
	v_lshlrev_b32_e32 v23, 2, v23
	s_nop 0
	v_cndmask_b32_e32 v21, v21, v16, vcc
	ds_bpermute_b32 v23, v23, v21
	v_cmp_lt_i32_e32 vcc, v24, v22
	s_waitcnt lgkmcnt(0)
	v_add_f32_e32 v23, v21, v23
	v_cndmask_b32_e32 v24, v24, v19, vcc
	v_cmp_gt_u32_e32 vcc, 2, v154
	v_lshlrev_b32_e32 v24, 2, v24
	s_nop 0
	v_cndmask_b32_e32 v21, v23, v21, vcc
	ds_bpermute_b32 v23, v24, v21
	v_add_u32_e32 v24, -8, v19
	v_cmp_lt_i32_e32 vcc, v24, v22
	s_waitcnt lgkmcnt(0)
	v_add_f32_e32 v23, v21, v23
	v_cndmask_b32_e32 v24, v24, v19, vcc
	v_cmp_gt_u32_e32 vcc, 4, v154
	v_lshlrev_b32_e32 v24, 2, v24
	s_nop 0
	v_cndmask_b32_e32 v21, v23, v21, vcc
	ds_bpermute_b32 v23, v24, v21
	v_add_u32_e32 v24, -16, v19
	v_cmp_lt_i32_e32 vcc, v24, v22
	s_waitcnt lgkmcnt(0)
	v_add_f32_e32 v23, v21, v23
	v_cndmask_b32_e32 v24, v24, v19, vcc
	v_cmp_gt_u32_e32 vcc, 8, v154
	v_lshlrev_b32_e32 v24, 2, v24
	s_nop 0
	v_cndmask_b32_e32 v21, v23, v21, vcc
	ds_bpermute_b32 v23, v24, v21
	v_subrev_u32_e32 v24, 32, v19
	v_cmp_lt_i32_e32 vcc, v24, v22
	s_nop 1
	v_cndmask_b32_e32 v19, v24, v19, vcc
	v_lshlrev_b32_e32 v22, 2, v19
	s_waitcnt lgkmcnt(0)
	v_add_f32_e32 v19, v21, v23
	v_cmp_gt_u32_e32 vcc, 16, v154
	s_nop 1
	v_cndmask_b32_e32 v19, v19, v21, vcc
	ds_bpermute_b32 v21, v22, v19
	v_cmp_eq_u32_e32 vcc, 63, v154
	s_waitcnt lgkmcnt(0)
	v_add_f32_e32 v21, v19, v21
	s_and_saveexec_b64 s[80:81], vcc
	s_lshl_b32 s74, s58, 2
	s_add_i32 s74, s74, 0x20040
	v_mov_b32_e32 v22, s74
	ds_write_b32 v22, v21
	s_or_b64 exec, exec, s[80:81]
	v_cndmask_b32_e64 v19, v21, v19, s[6:7]
	s_cmp_lt_u32 s76, 64
	v_sub_f32_e32 v19, v19, v16
	s_waitcnt lgkmcnt(0)
	s_barrier
	s_cbranch_scc1 .LBB0_264
	s_add_i32 s74, s58, -1
	s_cmp_lt_u32 s74, 7
	s_cbranch_scc1 .LBB0_261
	s_and_b32 s78, s58, 0x3fffff8
	s_mov_b32 s79, 0
	s_mov_b32 s80, 0x20040

; #define PG8_STAGE(bufoff, gbase, voff) do { _Pragma("unroll") for (int _i = 0; _i < 2; ++_i) \
;         __builtin_amdgcn_global_load_lds((const unsigned*)((const char*)(gbase) + (voff)[_i]), (PG8_LAS unsigned*)(lds + (bufoff) + ldsw + _i * 8192), 16, 0, 0); } while (0)
; #define PG8_WAIT_V(n) asm volatile("s_waitcnt vmcnt(" #n ")" ::: "memory")
; #define PG8_BAR __builtin_amdgcn_s_barrier()
; template <class Epi, class Sched, bool ALIGN_EPI = false, bool SP2 = false>
; __device__ __forceinline__ void gemm_phase(PG8_LAS unsigned char* lds, const Gemm g, const Sched& S, const Epi& E) {
;     ...
;     const int aoff = lds_byte(wr * 64 + fr, fq * 8), boff = lds_byte(wc * 32 + fr, fq * 8);
;     ...
;         PG8_WAIT_V(2); PG8_BAR;
;         PG8_STAGE(PG8_SB(1, 0), cB + kstep, voffB); PG8_STAGE(PG8_SA(1, 0), cA + kstep, voffA); PG8_STAGE(PG8_SB(1, 1), cB + hstep + kstep, voffB);
;         PG8_WAIT_V(6); PG8_BAR;
.Lscan_skip:
	s_waitcnt vmcnt(8)
.Lscan_join:
	s_barrier
	v_bfe_u32 v1, v12, 4, 2
	v_lshlrev_b32_e32 v157, 4, v1
	v_lshlrev_b32_e32 v3, 2, v12
	v_lshl_or_b32 v2, v156, 6, v157
	v_and_b32_e32 v3, 32, v3
	v_bitop3_b32 v4, v2, s13, v3 bitop3:0xde
	v_bitop3_b32 v158, v2, s17, v3 bitop3:0xde
	v_lshlrev_b32_e32 v2, 1, v12
	v_and_b32_e32 v3, 3, v12
	v_lshlrev_b32_e32 v0, 3, v1
	v_and_b32_e32 v2, 8, v2
	v_and_or_b32 v3, v14, 4, v3
	v_lshlrev_b32_e32 v1, 14, v1
	v_or3_b32 v167, v3, v2, v1
	v_lshlrev_b32_e32 v1, 8, v8
	v_and_b32_e32 v1, 0x18000, v1
	v_lshlrev_b32_e32 v2, 11, v13
	s_cmpk_lt_u32 s9, 0x100
	v_or3_b32 v1, v10, v1, v2
	s_cselect_b64 s[40:41], -1, 0
	s_and_b32 s13, s0, 0xffff
	v_add_u32_e32 v138, v1, v11
	v_lshlrev_b32_e32 v1, 11, v9
	s_mov_b32 s0, 0x38000
	v_mov_b32_e32 v3, 0x20000
	s_waitcnt vmcnt(6)
	v_bitop3_b32 v1, v1, s0, v3 bitop3:0xc8
	v_lshl_or_b32 v159, s67, 6, v157
	s_mov_b32 s23, 0x20000
	s_brev_b32 s22, -2
	v_or3_b32 v1, v10, v1, v2
	s_add_i32 s74, 0, 0x10000
	s_add_i32 s75, 0, 0x14000
	s_sext_i32_i8 s21, s8
	v_or_b32_e32 v160, 0x4000, v159
	v_or_b32_e32 v161, 0x8000, v159
	v_or_b32_e32 v162, 0xc000, v159
	v_or_b32_e32 v163, 0x20000, v159
	s_mov_b32 s71, 0x24000
	v_or_b32_e32 v164, 0x24000, v159
	v_or_b32_e32 v165, 0x28000, v159
	v_or_b32_e32 v166, 0x2c000, v159
	v_or_b32_e32 v168, 0xfffffa00, v159
	s_ashr_i32 s72, s26, 31
	s_mov_b32 s73, s26
	s_and_b32 s17, s1, 0xffff
	s_mov_b32 s18, s22
	s_mov_b32 s19, s23
	v_mov_b32_e32 v139, v137
	v_add_u32_e32 v140, v1, v11
	v_mov_b32_e32 v141, v137
	v_mov_b64_e32 v[142:143], 0x300
	v_mov_b64_e32 v[144:145], 0x2ff
	v_add_u32_e32 v169, s74, v158
	v_add_u32_e32 v170, s75, v158
	v_add_u32_e32 v171, 0, v4
	s_movk_i32 s76, 0x7fff
	s_movk_i32 s77, 0x1000
	s_movk_i32 s78, 0x3000
	s_movk_i32 s79, 0x5000
	s_movk_i32 s80, 0x7000
	s_mov_b32 s81, 0x21000
	s_mov_b32 s82, 0x22000
	s_mov_b32 s83, 0x23000
	s_mov_b32 s84, 0x25000
	s_mov_b32 s85, 0x26000
	s_mov_b32 s86, 0x27000
	s_brev_b32 s87, 32
	v_lshlrev_b32_e32 v172, 2, v0
	v_mov_b32_e32 v173, 0x358637bd
	s_mov_b32 s88, 0x800000
	v_mov_b32_e32 v175, 0x3e38aa3b
	v_mbcnt_hi_u32_b32 v176, -1, v209
	s_barrier
	s_branch .LBB0_271

; #define PG8_STAGE(bufoff, gbase, voff) do { _Pragma("unroll") for (int _i = 0; _i < 2; ++_i) \
;         __builtin_amdgcn_global_load_lds((const unsigned*)((const char*)(gbase) + (voff)[_i]), (PG8_LAS unsigned*)(lds + (bufoff) + ldsw + _i * 8192), 16, 0, 0); } while (0)
; #define PG8_WAIT_V(n) asm volatile("s_waitcnt vmcnt(" #n ")" ::: "memory")
; #define PG8_BAR __builtin_amdgcn_s_barrier()
; template <class Epi, class Sched, bool ALIGN_EPI = false, bool SP2 = false>
; __device__ __forceinline__ void gemm_phase(PG8_LAS unsigned char* lds, const Gemm g, const Sched& S, const Epi& E) {
;     ...
;         PG8_STAGE(PG8_SB(0, 0), cB, voffB); PG8_STAGE(PG8_SB(0, 1), cB + hstep, voffB); PG8_STAGE(PG8_SA(0, 0), cA, voffA); PG8_STAGE(PG8_SA(0, 1), cA + hstep, voffA);
;         if (wr == 1) PG8_BAR;
;         PG8_WAIT_V(2); PG8_BAR;
;         PG8_STAGE(PG8_SB(1, 0), cB + kstep, voffB); PG8_STAGE(PG8_SA(1, 0), cA + kstep, voffA); PG8_STAGE(PG8_SB(1, 1), cB + hstep + kstep, voffB);
;         PG8_WAIT_V(6); PG8_BAR;
.LBB0_448:
	s_add_u32 s12, s36, 0x4000000
	s_addc_u32 s0, s37, 0
	s_add_u32 s16, s36, 0x2000000
	s_addc_u32 s1, s37, 0
	s_add_u32 s40, s36, 0x1f00000
	s_addc_u32 s41, s37, 0
	s_add_u32 s20, s36, 0x1e80000
	s_mov_b64 s[42:43], 0x80
	s_addc_u32 s11, s37, 0
	s_and_b32 s63, s8, 3
	s_add_i32 m0, s28, 0x18000
	v_lshl_add_u64 v[6:7], v[6:7], 0, s[42:43]
	s_lshl_b32 s64, s9, 6
	s_lshl_b32 s13, s9, 13
	s_lshl_b32 s15, s63, 12
	global_load_lds_dwordx4 v[6:7], off
	v_lshl_add_u64 v[4:5], v[4:5], 0, s[42:43]
	s_add_i32 m0, s28, 0x1a000
	s_add_i32 s65, s28, 0x8000
	s_add_i32 s66, s28, 0xa000
	global_load_lds_dwordx4 v[4:5], off
	v_lshl_add_u64 v[0:1], v[0:1], 0, s[42:43]
	s_mov_b32 m0, s65
	s_add_u32 s8, s56, 0x40080
	global_load_lds_dwordx4 v[0:1], off
	v_lshl_add_u64 v[0:1], v[2:3], 0, s[42:43]
	s_mov_b32 m0, s66
	s_addc_u32 s9, s57, 0
	global_load_lds_dwordx4 v[0:1], off
	s_add_i32 m0, s28, 0x1c000
	v_lshl_add_u64 v[0:1], s[8:9], 0, v[212:213]
	global_load_lds_dwordx4 v[0:1], off
	v_lshl_add_u64 v[0:1], s[8:9], 0, v[216:217]
	s_add_i32 m0, s28, 0x1e000
	v_and_b32_e32 v246, 15, v9
	global_load_lds_dwordx4 v[0:1], off
	s_waitcnt vmcnt(8)
	s_barrier
	v_bfe_u32 v0, v9, 4, 2
	v_lshlrev_b32_e32 v1, 3, v0
	v_lshlrev_b32_e32 v2, 4, v0
	v_cmp_eq_u32_e64 s[8:9], 0, v0
	v_lshlrev_b32_e32 v0, 8, v8
	v_lshlrev_b32_e32 v3, 2, v9
	v_lshl_or_b32 v248, s63, 5, v1
	v_and_b32_e32 v0, 0x18000, v0
	v_lshlrev_b32_e32 v1, 11, v12
	v_lshl_or_b32 v2, v246, 6, v2
	v_and_b32_e32 v3, 32, v3
	s_cmpk_lt_u32 s10, 0x100
	v_or3_b32 v0, v10, v0, v1
	v_bitop3_b32 v4, v2, s13, v3 bitop3:0xde
	v_bitop3_b32 v247, v2, s15, v3 bitop3:0xde
	s_cselect_b64 s[44:45], -1, 0
	s_and_b32 s13, s0, 0xffff
	v_add_u32_e32 v220, v0, v11
	v_lshlrev_b32_e32 v0, 11, v13
	s_mov_b32 s0, 0x38000
	v_mov_b32_e32 v2, 0x20000
	s_waitcnt vmcnt(6)
	v_bitop3_b32 v0, v0, s0, v2 bitop3:0xc8
	v_or3_b32 v0, v10, v0, v1
	s_add_i32 s70, 0, 0x10000
	s_add_i32 s71, 0, 0x14000
	s_ashr_i32 s67, s26, 31
	s_mov_b32 s68, s26
	s_ashr_i32 s69, s2, 31
	s_and_b32 s17, s1, 0xffff
	s_mov_b32 s19, 0x20000
	s_brev_b32 s18, -2
	s_and_b32 s21, s11, 0xffff
	v_mov_b32_e32 v221, v219
	v_add_u32_e32 v222, v0, v11
	v_mov_b32_e32 v223, v219
	v_mov_b64_e32 v[224:225], 0x100
	v_mov_b64_e32 v[226:227], 0xff
	v_add_u32_e32 v249, s70, v247
	v_add_u32_e32 v250, s71, v247
	v_add_u32_e32 v251, 0, v4
	v_mbcnt_hi_u32_b32 v252, -1, v209
	s_movk_i32 s72, 0x7ef
	s_movk_i32 s73, 0x7df
	s_movk_i32 s74, 0x7ff
	s_barrier
	s_branch .LBB0_451

; #define PG8_STAGE(bufoff, gbase, voff) do { _Pragma("unroll") for (int _i = 0; _i < 2; ++_i) \
;         __builtin_amdgcn_global_load_lds((const unsigned*)((const char*)(gbase) + (voff)[_i]), (PG8_LAS unsigned*)(lds + (bufoff) + ldsw + _i * 8192), 16, 0, 0); } while (0)
; #define PG8_WAIT_V(n) asm volatile("s_waitcnt vmcnt(" #n ")" ::: "memory")
; #define PG8_BAR __builtin_amdgcn_s_barrier()
; template <class Epi, class Sched, bool ALIGN_EPI = false, bool SP2 = false>
; __device__ __forceinline__ void gemm_phase(PG8_LAS unsigned char* lds, const Gemm g, const Sched& S, const Epi& E) {
;     ...
;         PG8_STAGE(PG8_SB(0, 0), cB, voffB); PG8_STAGE(PG8_SB(0, 1), cB + hstep, voffB); PG8_STAGE(PG8_SA(0, 0), cA, voffA); PG8_STAGE(PG8_SA(0, 1), cA + hstep, voffA);
;         if (wr == 1) PG8_BAR;
;         PG8_WAIT_V(2); PG8_BAR;
;         PG8_STAGE(PG8_SB(1, 0), cB + kstep, voffB); PG8_STAGE(PG8_SA(1, 0), cA + kstep, voffA); PG8_STAGE(PG8_SB(1, 1), cB + hstep + kstep, voffB);
;         PG8_WAIT_V(6); PG8_BAR;
.LBB0_560:
	s_add_u32 s36, s8, 0x1f00000
	s_addc_u32 s37, s9, 0
	s_add_u32 s81, s8, 0x40000
	s_addc_u32 s82, s9, 0
	s_add_u32 s38, s8, 0xa000000
	s_addc_u32 s39, s9, 0
	s_lshl_b32 s1, s5, 5
	s_mov_b64 s[40:41], 0x80
	s_and_b32 s84, s1, 0x60
	s_add_i32 m0, s69, 0x18000
	v_lshl_add_u64 v[6:7], v[6:7], 0, s[40:41]
	s_lshl_b32 s83, s74, 6
	s_lshl_b32 s0, s74, 13
	s_lshl_b32 s1, s84, 7
	global_load_lds_dwordx4 v[6:7], off
	v_lshl_add_u64 v[4:5], v[4:5], 0, s[40:41]
	s_add_i32 m0, s69, 0x1a000
	s_add_i32 s85, s69, 0x8000
	s_add_i32 s86, s69, 0xa000
	global_load_lds_dwordx4 v[4:5], off
	v_lshl_add_u64 v[2:3], v[2:3], 0, s[40:41]
	s_mov_b32 m0, s85
	s_add_u32 s6, s12, 0x40080
	global_load_lds_dwordx4 v[2:3], off
	v_lshl_add_u64 v[0:1], v[0:1], 0, s[40:41]
	s_mov_b32 m0, s86
	s_addc_u32 s7, s13, 0
	global_load_lds_dwordx4 v[0:1], off
	s_add_i32 m0, s69, 0x1c000
	v_lshl_add_u64 v[0:1], s[6:7], 0, v[178:179]
	global_load_lds_dwordx4 v[0:1], off
	v_lshl_add_u64 v[0:1], s[6:7], 0, v[182:183]
	s_add_i32 m0, s69, 0x1e000
	s_cmpk_lt_u32 s4, 0x100
	global_load_lds_dwordx4 v[0:1], off
	s_waitcnt vmcnt(8)
	s_barrier
	v_bfe_u32 v222, v9, 4, 2
	s_cselect_b64 s[42:43], -1, 0
	s_cmpk_gt_u32 s4, 0xff
	v_and_b32_e32 v254, 15, v9
	v_lshlrev_b32_e32 v0, 4, v222
	v_lshlrev_b32_e32 v1, 2, v9
	s_cselect_b64 s[44:45], -1, 0
	s_lshl_b32 s89, s74, 1
	v_lshl_or_b32 v0, v254, 6, v0
	v_and_b32_e32 v1, 32, v1
	s_mul_i32 s4, s74, 0x2c00
	s_add_i32 s90, s89, 4
	v_bitop3_b32 v2, v0, s0, v1 bitop3:0xde
	s_lshl_b32 s0, s74, 11
	s_add_i32 s6, s4, 0x1600
	s_mul_i32 s8, s90, 0x1600
	s_ashr_i32 s7, s6, 31
	s_add_i32 s10, s8, 0x1600
	s_add_i32 s16, s4, 0x6e00
	s_add_i32 s96, s0, 0
	s_lshl_b32 s88, s74, 16
	s_ashr_i32 s11, s10, 31
	s_ashr_i32 s5, s4, 31
	s_lshl_b32 s91, s74, 12
	s_ashr_i32 s9, s8, 31
	s_ashr_i32 s17, s16, 31
	s_ashr_i32 s92, s26, 31
	s_ashr_i32 s94, s2, 31
	s_add_i32 s95, s96, 0x20040
	s_add_i32 s96, s96, 0x1f840
	s_lshl_b64 s[6:7], s[6:7], 2
	s_add_u32 s46, s81, s6
	s_addc_u32 s47, s82, s7
	s_lshl_b64 s[6:7], s[10:11], 2
	s_add_u32 s0, s81, s6
	v_bitop3_b32 v223, v0, s1, v1 bitop3:0xde
	s_addc_u32 s1, s82, s7
	s_lshl_b64 s[4:5], s[4:5], 2
	s_add_u32 s50, s81, s4
	v_lshlrev_b32_e32 v0, 8, v8
	s_addc_u32 s51, s82, s5
	s_lshl_b64 s[4:5], s[8:9], 2
	v_and_b32_e32 v0, 0x18000, v0
	v_lshlrev_b32_e32 v1, 11, v12
	v_writelane_b32 v255, s0, 9
	s_add_u32 s52, s81, s4
	v_or3_b32 v0, v10, v0, v1
	v_writelane_b32 v255, s1, 10
	s_addc_u32 s53, s82, s5
	s_lshl_b64 s[4:5], s[16:17], 2
	v_add_u32_e32 v186, v0, v11
	v_lshlrev_b32_e32 v0, 11, v13
	s_mov_b32 s0, 0x38000
	v_mov_b32_e32 v3, 0x20000
	s_waitcnt vmcnt(6)
	s_add_u32 s54, s81, s4
	v_bitop3_b32 v0, v0, s0, v3 bitop3:0xc8
	s_addc_u32 s55, s82, s5
	v_or3_b32 v0, v10, v0, v1
	s_add_i32 s97, 0, 0x10000
	s_add_i32 s72, 0, 0x14000
	s_mov_b32 s87, 0x8000
	s_mov_b32 s93, s26
	v_mov_b32_e32 v187, v185
	v_add_u32_e32 v188, v0, v11
	v_mov_b32_e32 v189, v185
	v_mov_b64_e32 v[248:249], 0x596
	v_mov_b64_e32 v[194:195], 0x595
	v_add_u32_e32 v224, s97, v223
	v_add_u32_e32 v225, s72, v223
	v_add_u32_e32 v226, 0, v2
	s_mov_b32 s56, 0x3a800000
	s_mov_b32 s58, 0x358637bd
	s_mov_b32 s6, 0x800000
	s_mov_b64 s[60:61], 0x2c00
	s_movk_i32 s7, 0xb00
	s_movk_i32 s4, 0x7e00
	s_movk_i32 s5, 0x7e0
	v_mbcnt_hi_u32_b32 v209, -1, v209
	s_barrier
	s_branch .LBB0_563

; #define PG8_STAGE(bufoff, gbase, voff) do { _Pragma("unroll") for (int _i = 0; _i < 2; ++_i) \
;         __builtin_amdgcn_global_load_lds((const unsigned*)((const char*)(gbase) + (voff)[_i]), (PG8_LAS unsigned*)(lds + (bufoff) + ldsw + _i * 8192), 16, 0, 0); } while (0)
; #define PG8_WAIT_V(n) asm volatile("s_waitcnt vmcnt(" #n ")" ::: "memory")
; #define PG8_BAR __builtin_amdgcn_s_barrier()
; template <class Epi, class Sched, bool ALIGN_EPI = false, bool SP2 = false>
; __device__ __forceinline__ void gemm_phase(PG8_LAS unsigned char* lds, const Gemm g, const Sched& S, const Epi& E) {
;     ...
;         PG8_STAGE(PG8_SB(0, 0), cB, voffB); PG8_STAGE(PG8_SB(0, 1), cB + hstep, voffB); PG8_STAGE(PG8_SA(0, 0), cA, voffA); PG8_STAGE(PG8_SA(0, 1), cA + hstep, voffA);
;         if (wr == 1) PG8_BAR;
;         PG8_WAIT_V(2); PG8_BAR;
;         PG8_STAGE(PG8_SB(1, 0), cB + kstep, voffB); PG8_STAGE(PG8_SA(1, 0), cA + kstep, voffA); PG8_STAGE(PG8_SB(1, 1), cB + hstep + kstep, voffB);
;         PG8_WAIT_V(6); PG8_BAR;
.LBB0_660:
	s_add_u32 s12, s10, 0x4000000
	s_addc_u32 s13, s11, 0
	s_lshl_b32 s5, s5, 5
	s_mov_b64 s[14:15], 0x80
	s_and_b32 s5, s5, 0x60
	s_add_i32 m0, s35, 0x18000
	v_lshl_add_u64 v[6:7], v[6:7], 0, s[14:15]
	s_lshl_b32 s18, s0, 13
	s_lshl_b32 s19, s5, 7
	global_load_lds_dwordx4 v[6:7], off
	v_lshl_add_u64 v[4:5], v[4:5], 0, s[14:15]
	s_add_i32 m0, s35, 0x1a000
	s_add_i32 s40, s35, 0x8000
	s_add_i32 s41, s35, 0xa000
	global_load_lds_dwordx4 v[4:5], off
	v_lshl_add_u64 v[0:1], v[0:1], 0, s[14:15]
	s_mov_b32 m0, s40
	s_add_u32 s16, s24, 0xb0080
	global_load_lds_dwordx4 v[0:1], off
	v_lshl_add_u64 v[0:1], v[2:3], 0, s[14:15]
	s_mov_b32 m0, s41
	s_addc_u32 s17, s25, 0
	global_load_lds_dwordx4 v[0:1], off
	s_add_i32 m0, s35, 0x1c000
	v_lshl_add_u64 v[0:1], s[16:17], 0, v[146:147]
	global_load_lds_dwordx4 v[0:1], off
	v_lshl_add_u64 v[0:1], s[16:17], 0, v[150:151]
	s_add_i32 m0, s35, 0x1e000
	v_lshlrev_b32_e32 v2, 2, v208
	global_load_lds_dwordx4 v[0:1], off
	s_waitcnt vmcnt(8)
	s_barrier
	v_and_b32_e32 v0, 15, v208
	v_lshlrev_b32_e32 v1, 1, v10
	v_lshl_or_b32 v1, v0, 6, v1
	v_lshlrev_b32_e32 v0, 10, v0
	v_and_b32_e32 v2, 32, v2
	s_waitcnt vmcnt(6)
	s_cmpk_lt_u32 s4, 0x100
	v_lshl_or_b32 v169, s0, 16, v0
	v_add_u16_e32 v0, v8, v9
	v_bitop3_b32 v3, v1, s18, v2 bitop3:0xde
	v_bitop3_b32 v168, v1, s19, v2 bitop3:0xde
	s_cselect_b64 s[16:17], -1, 0
	v_lshrrev_b16_e32 v0, 1, v0
	s_add_i32 s43, 0, 0x10000
	s_add_i32 s44, 0, 0x14000
	s_sext_i32_i8 s49, s1
	s_ashr_i32 s42, s26, 31
	v_or_b32_e32 v170, s5, v10
	v_add_lshl_u32 v154, v11, v0, 1
	v_mov_b32_e32 v155, v153
	v_add_lshl_u32 v156, v12, v0, 1
	v_mov_b32_e32 v157, v153
	v_mov_b64_e32 v[158:159], 0x100
	v_mov_b64_e32 v[160:161], 0xff
	v_add_u32_e32 v171, s43, v168
	v_add_u32_e32 v172, s44, v168
	v_add_u32_e32 v173, 0, v3
	s_mov_b64 s[18:19], 0x5000
	s_movk_i32 s45, 0x5000
	s_barrier
	s_branch .LBB0_663
